# NSA sel/win tile bodies: all K fragment reads issued up front (in addition to V reads in the QK MFMA shadow)
# baseline (speedup 1.0000x reference)
; __device__ __forceinline__ f32x16 mfma32(bf16x8 a, bf16x8 b, f32x16 c) { return __builtin_amdgcn_mfma_f32_32x32x16_bf16(a, b, c, 0, 0, 0); }
; __device__ __forceinline__ s16x4 tr16(lptr p) { return __builtin_bit_cast(s16x4, __builtin_amdgcn_ds_read_tr16_b64_v4i16((LAS v4i16_t*)p)); }
; template <int MODE> ...
;     ...
;         const lptr Kt = L + A_KT + buf * 9216, Vt = L + A_VT + vcur * 12288;
;         f32x16 s0, s1;
; #pragma unroll
;         for (int s4 = 0; s4 < 4; ++s4) {
;             const bf16x8 a0 = lds_ld<bf16x8>(Kt + n * KP + s4 * 32 + hl * 16);
;             const bf16x8 a1 = lds_ld<bf16x8>(Kt + (32 + n) * KP + s4 * 32 + hl * 16);
;             if (s4 == 0) { s0 = mfma32(a0, qf[0], negm); s1 = mfma32(a1, qf[0], negm); }
;             else { s0 = mfma32(a0, qf[s4], s0); s1 = mfma32(a1, qf[s4], s1); }
;         }
;     ...
;             const lptr vb_ = Vt + (4 * hl + q4) * VP + 32 * blk + 8 * p4;
; #pragma unroll
;             for (int c_ = 0; c_ < 2; ++c_)
; #pragma unroll
;                 for (int ks_ = 0; ks_ < 4; ++ks_) {
;                     const s16x4 lo_ = tr16(vb_ + (16 * ks_) * VP + 64 * c_), hi_ = tr16(vb_ + (16 * ks_ + 8) * VP + 64 * c_);
;                     const bf16x8 vf_ = {lo_[0], lo_[1], lo_[2], lo_[3], hi_[0], hi_[1], hi_[2], hi_[3]};
;                     o[c_] = mfma32(vf_, pf[ks_], o[c_]);
;                 }
.LBB0_310:
	v_sub_co_u32_e64 v10, vcc, s0, 32
	v_lshrrev_b32_e32 v0, s0, v160
	v_lshrrev_b32_e32 v10, v10, v161
	v_cndmask_b32_e32 v0, v10, v0, vcc
	v_and_b32_e32 v0, 1, v0
	v_cmp_eq_u32_e64 s[38:39], 1, v0
	v_cmp_ne_u32_e32 vcc, 0, v0
	s_cbranch_vccz .LBB0_318
	v_add_u32_e32 v14, v182, v183
	v_add_u32_e32 v0, v184, v183
	s_lshl_b32 s7, s0, 6
	v_cmp_ge_i32_e32 vcc, s7, v179
	v_add_u32_e32 v212, v186, v187
	ds_read_b128 v[64:67], v14 offset:0
	ds_read_b128 v[68:71], v0 offset:0
	ds_read_b128 v[72:75], v14 offset:32
	ds_read_b128 v[76:79], v0 offset:32
	ds_read_b128 v[80:83], v14 offset:64
	ds_read_b128 v[84:87], v0 offset:64
	ds_read_b128 v[88:91], v14 offset:96
	ds_read_b128 v[92:95], v0 offset:96
	s_waitcnt lgkmcnt(7)
	v_mfma_f32_32x32x16_bf16 v[112:127], v[64:67], v[128:131], v[48:63]
	ds_read_b64_tr_b16 v[196:197], v212 offset:18432
	ds_read_b64_tr_b16 v[198:199], v212 offset:19968
	s_waitcnt lgkmcnt(8)
	v_mfma_f32_32x32x16_bf16 v[96:111], v[68:71], v[128:131], v[48:63]
	ds_read_b64_tr_b16 v[200:201], v212 offset:21504
	ds_read_b64_tr_b16 v[202:203], v212 offset:23040
	s_waitcnt lgkmcnt(9)
	v_mfma_f32_32x32x16_bf16 v[112:127], v[72:75], v[132:135], v[112:127]
	ds_read_b64_tr_b16 v[204:205], v212 offset:24576
	ds_read_b64_tr_b16 v[206:207], v212 offset:26112
	s_waitcnt lgkmcnt(10)
	v_mfma_f32_32x32x16_bf16 v[96:111], v[76:79], v[132:135], v[96:111]
	ds_read_b64_tr_b16 v[208:209], v212 offset:27648
	ds_read_b64_tr_b16 v[210:211], v212 offset:29184
	s_waitcnt lgkmcnt(11)
	v_mfma_f32_32x32x16_bf16 v[112:127], v[80:83], v[136:139], v[112:127]
	ds_read_b64_tr_b16 v[238:239], v212 offset:18496
	ds_read_b64_tr_b16 v[240:241], v212 offset:20032
	s_waitcnt lgkmcnt(12)
	v_mfma_f32_32x32x16_bf16 v[96:111], v[84:87], v[136:139], v[96:111]
	ds_read_b64_tr_b16 v[242:243], v212 offset:21568
	ds_read_b64_tr_b16 v[244:245], v212 offset:23104
	s_waitcnt lgkmcnt(13)
	v_mfma_f32_32x32x16_bf16 v[112:127], v[88:91], v[140:143], v[112:127]
	ds_read_b64_tr_b16 v[246:247], v212 offset:24640
	ds_read_b64_tr_b16 v[248:249], v212 offset:26176
	s_waitcnt lgkmcnt(14)
	v_mfma_f32_32x32x16_bf16 v[96:111], v[92:95], v[140:143], v[96:111]
	ds_read_b64_tr_b16 v[234:235], v212 offset:27712
	ds_read_b64_tr_b16 v[236:237], v212 offset:29248
	s_and_saveexec_b64 s[0:1], vcc
	s_xor_b64 s[0:1], exec, s[0:1]
	s_cbranch_execz .LBB0_313
; template <int MODE> ...
;     ...
;         } else if (MODE == MODE_WIN || MODE == MODE_SEL) {
;             const int dbase = t - kbase;
;             const lptr tb = L + tabofs + (dbase + TAB0 - 63) * 4;
; #pragma unroll
;             for (int kb = 0; kb < 2; ++kb)
; #pragma unroll
;                 for (int a = 0; a < 4; ++a)
; #pragma unroll
;                     for (int e = 0; e < 4; ++e) {
;                         const int r = 4 * a + e, off = 32 * kb + 8 * a + e; const int d = dbase - off;
;                         const float bsv = far ? tab128 : lds_ld<float>(tb + 4 * (63 - off));
;                         const bool ok = (MODE == MODE_WIN) ? ((unsigned)d < (unsigned)W) : (selbit && d >= 0);
;                         const float sv = kb ? s1[r] : s0[r];
;                         const float x = ok ? sv * SC2 + bsv : -INFINITY;
;                         if (kb) s1[r] = x; else s0[r] = x;
;                     }
	v_or_b32_e32 v0, s7, v185
	v_sub_u32_e32 v0, v229, v0
	v_lshl_add_u32 v10, v0, 2, v230
	ds_read2_b32 v[12:13], v10 offset0:127 offset1:128
	v_cmp_lt_i32_e32 vcc, -1, v0
	s_and_b64 vcc, vcc, s[38:39]
	s_waitcnt lgkmcnt(0)
	s_nop 0
	v_fmamk_f32 v11, v112, 0x3e38aa3b, v13
	v_cndmask_b32_e32 v64, v220, v11, vcc
	v_cmp_lt_i32_e32 vcc, 0, v0
	s_and_b64 vcc, vcc, s[38:39]
	v_fmac_f32_e32 v12, 0x3e38aa3b, v113
	v_cndmask_b32_e32 v65, v220, v12, vcc
	ds_read2_b32 v[12:13], v10 offset0:125 offset1:126
	v_cmp_lt_i32_e32 vcc, 1, v0
	s_and_b64 vcc, vcc, s[38:39]
	s_waitcnt lgkmcnt(0)
	v_fmamk_f32 v11, v114, 0x3e38aa3b, v13
	v_cndmask_b32_e32 v66, v220, v11, vcc
	v_cmp_lt_i32_e32 vcc, 2, v0
	s_and_b64 vcc, vcc, s[38:39]
	v_fmac_f32_e32 v12, 0x3e38aa3b, v115
	v_cndmask_b32_e32 v67, v220, v12, vcc
	ds_read2_b32 v[12:13], v10 offset0:119 offset1:120
	v_cmp_lt_i32_e32 vcc, 7, v0
	s_and_b64 vcc, vcc, s[38:39]
	s_waitcnt lgkmcnt(0)
	v_fmamk_f32 v11, v116, 0x3e38aa3b, v13
	v_cndmask_b32_e32 v68, v220, v11, vcc
	v_cmp_lt_i32_e32 vcc, 8, v0
	s_and_b64 vcc, vcc, s[38:39]
	v_fmac_f32_e32 v12, 0x3e38aa3b, v117
	v_cndmask_b32_e32 v69, v220, v12, vcc
	ds_read2_b32 v[12:13], v10 offset0:117 offset1:118
	v_cmp_lt_i32_e32 vcc, 9, v0
	s_and_b64 vcc, vcc, s[38:39]
	s_waitcnt lgkmcnt(0)
	v_fmamk_f32 v11, v118, 0x3e38aa3b, v13
	v_cndmask_b32_e32 v70, v220, v11, vcc
	v_cmp_lt_i32_e32 vcc, 10, v0
	s_and_b64 vcc, vcc, s[38:39]
	v_fmac_f32_e32 v12, 0x3e38aa3b, v119
	v_cndmask_b32_e32 v71, v220, v12, vcc
	ds_read2_b32 v[12:13], v10 offset0:111 offset1:112
	v_cmp_lt_i32_e32 vcc, 15, v0
	s_and_b64 vcc, vcc, s[38:39]
	s_waitcnt lgkmcnt(0)
	v_fmamk_f32 v11, v120, 0x3e38aa3b, v13
	v_cndmask_b32_e32 v72, v220, v11, vcc
	v_cmp_lt_i32_e32 vcc, 16, v0
	s_and_b64 vcc, vcc, s[38:39]
	v_fmac_f32_e32 v12, 0x3e38aa3b, v121
	v_cndmask_b32_e32 v73, v220, v12, vcc
	ds_read2_b32 v[12:13], v10 offset0:109 offset1:110
	v_cmp_lt_i32_e32 vcc, 17, v0
	s_and_b64 vcc, vcc, s[38:39]
	s_waitcnt lgkmcnt(0)
	v_fmamk_f32 v11, v122, 0x3e38aa3b, v13
	v_cndmask_b32_e32 v74, v220, v11, vcc
	v_cmp_lt_i32_e32 vcc, 18, v0
	s_and_b64 vcc, vcc, s[38:39]
	v_fmac_f32_e32 v12, 0x3e38aa3b, v123
	v_cndmask_b32_e32 v75, v220, v12, vcc
	ds_read2_b32 v[12:13], v10 offset0:103 offset1:104
	v_cmp_lt_i32_e32 vcc, 23, v0
	s_and_b64 vcc, vcc, s[38:39]
	s_waitcnt lgkmcnt(0)
	v_fmamk_f32 v11, v124, 0x3e38aa3b, v13
	v_cndmask_b32_e32 v76, v220, v11, vcc
	v_cmp_lt_i32_e32 vcc, 24, v0
	s_and_b64 vcc, vcc, s[38:39]
	v_fmac_f32_e32 v12, 0x3e38aa3b, v125
	v_cndmask_b32_e32 v77, v220, v12, vcc
	ds_read2_b32 v[12:13], v10 offset0:101 offset1:102
	v_cmp_lt_i32_e32 vcc, 25, v0
	s_and_b64 vcc, vcc, s[38:39]
	s_waitcnt lgkmcnt(0)
	v_fmamk_f32 v11, v126, 0x3e38aa3b, v13
	v_cndmask_b32_e32 v78, v220, v11, vcc
	v_cmp_lt_i32_e32 vcc, 26, v0
	s_and_b64 vcc, vcc, s[38:39]
	v_fmac_f32_e32 v12, 0x3e38aa3b, v127
	v_cndmask_b32_e32 v79, v220, v12, vcc
	ds_read2_b32 v[12:13], v10 offset0:95 offset1:96
	v_cmp_lt_i32_e32 vcc, 31, v0
	s_and_b64 vcc, vcc, s[38:39]
	s_waitcnt lgkmcnt(0)
	v_fmamk_f32 v11, v96, 0x3e38aa3b, v13
	v_cndmask_b32_e32 v80, v220, v11, vcc
	v_cmp_lt_i32_e32 vcc, 32, v0
	s_and_b64 vcc, vcc, s[38:39]
	v_fmac_f32_e32 v12, 0x3e38aa3b, v97
	v_cndmask_b32_e32 v81, v220, v12, vcc
	ds_read2_b32 v[12:13], v10 offset0:93 offset1:94
	v_cmp_lt_i32_e32 vcc, 33, v0
	s_and_b64 vcc, vcc, s[38:39]
	s_waitcnt lgkmcnt(0)
	v_fmamk_f32 v11, v98, 0x3e38aa3b, v13
	v_cndmask_b32_e32 v82, v220, v11, vcc
	v_cmp_lt_i32_e32 vcc, 34, v0
	s_and_b64 vcc, vcc, s[38:39]
	v_fmac_f32_e32 v12, 0x3e38aa3b, v99
	v_cndmask_b32_e32 v83, v220, v12, vcc
	ds_read2_b32 v[12:13], v10 offset0:87 offset1:88
	v_cmp_lt_i32_e32 vcc, 39, v0
	s_and_b64 vcc, vcc, s[38:39]
	s_waitcnt lgkmcnt(0)
	v_fmamk_f32 v11, v100, 0x3e38aa3b, v13
	v_cndmask_b32_e32 v84, v220, v11, vcc
	v_cmp_lt_i32_e32 vcc, 40, v0
	s_and_b64 vcc, vcc, s[38:39]
	v_fmac_f32_e32 v12, 0x3e38aa3b, v101
	v_cndmask_b32_e32 v85, v220, v12, vcc
	ds_read2_b32 v[12:13], v10 offset0:85 offset1:86
	v_cmp_lt_i32_e32 vcc, 41, v0
	s_and_b64 vcc, vcc, s[38:39]
	s_waitcnt lgkmcnt(0)
	v_fmamk_f32 v11, v102, 0x3e38aa3b, v13
	v_cndmask_b32_e32 v86, v220, v11, vcc
	v_cmp_lt_i32_e32 vcc, 42, v0
	s_and_b64 vcc, vcc, s[38:39]
	v_fmac_f32_e32 v12, 0x3e38aa3b, v103
	v_cndmask_b32_e32 v87, v220, v12, vcc
	ds_read2_b32 v[12:13], v10 offset0:79 offset1:80
	v_cmp_lt_i32_e32 vcc, 47, v0
	s_and_b64 vcc, vcc, s[38:39]
	s_waitcnt lgkmcnt(0)
	v_fmamk_f32 v11, v104, 0x3e38aa3b, v13
	v_cndmask_b32_e32 v88, v220, v11, vcc
	v_cmp_lt_i32_e32 vcc, 48, v0
	s_and_b64 vcc, vcc, s[38:39]
	v_fmac_f32_e32 v12, 0x3e38aa3b, v105
	v_cndmask_b32_e32 v89, v220, v12, vcc
	ds_read2_b32 v[12:13], v10 offset0:77 offset1:78
	v_cmp_lt_i32_e32 vcc, 49, v0
	s_and_b64 vcc, vcc, s[38:39]
	s_waitcnt lgkmcnt(0)
	v_fmamk_f32 v11, v106, 0x3e38aa3b, v13
	v_cndmask_b32_e32 v90, v220, v11, vcc
	v_cmp_lt_i32_e32 vcc, 50, v0
	s_and_b64 vcc, vcc, s[38:39]
	v_fmac_f32_e32 v12, 0x3e38aa3b, v107
	v_cndmask_b32_e32 v91, v220, v12, vcc
	ds_read2_b32 v[12:13], v10 offset0:71 offset1:72
	v_cmp_lt_i32_e32 vcc, 55, v0
	s_and_b64 vcc, vcc, s[38:39]
	s_waitcnt lgkmcnt(0)
	v_fmamk_f32 v11, v108, 0x3e38aa3b, v13
	v_cndmask_b32_e32 v92, v220, v11, vcc
	ds_read2_b32 v[10:11], v10 offset0:69 offset1:70
	v_cmp_lt_i32_e32 vcc, 56, v0
	s_and_b64 vcc, vcc, s[38:39]
	v_fmac_f32_e32 v12, 0x3e38aa3b, v109
	v_cndmask_b32_e32 v93, v220, v12, vcc
	v_cmp_lt_i32_e32 vcc, 57, v0
	s_and_b64 vcc, vcc, s[38:39]
	s_waitcnt lgkmcnt(0)
	v_fmamk_f32 v11, v110, 0x3e38aa3b, v11
	v_cndmask_b32_e32 v94, v220, v11, vcc
	v_cmp_lt_i32_e32 vcc, 58, v0
	s_and_b64 vcc, vcc, s[38:39]
	v_fmac_f32_e32 v10, 0x3e38aa3b, v111
	v_cndmask_b32_e32 v95, v220, v10, vcc

; __device__ __forceinline__ f32x16 mfma32(bf16x8 a, bf16x8 b, f32x16 c) { return __builtin_amdgcn_mfma_f32_32x32x16_bf16(a, b, c, 0, 0, 0); }
; __device__ __forceinline__ s16x4 tr16(lptr p) { return __builtin_bit_cast(s16x4, __builtin_amdgcn_ds_read_tr16_b64_v4i16((LAS v4i16_t*)p)); }
; template <int MODE> ...
;     ...
;         const lptr Kt = L + A_KT + buf * 9216, Vt = L + A_VT + vcur * 12288;
;         f32x16 s0, s1;
; #pragma unroll
;         for (int s4 = 0; s4 < 4; ++s4) {
;             const bf16x8 a0 = lds_ld<bf16x8>(Kt + n * KP + s4 * 32 + hl * 16);
;             const bf16x8 a1 = lds_ld<bf16x8>(Kt + (32 + n) * KP + s4 * 32 + hl * 16);
;             if (s4 == 0) { s0 = mfma32(a0, qf[0], negm); s1 = mfma32(a1, qf[0], negm); }
;             else { s0 = mfma32(a0, qf[s4], s0); s1 = mfma32(a1, qf[s4], s1); }
;         }
;     ...
;             const lptr vb_ = Vt + (4 * hl + q4) * VP + 32 * blk + 8 * p4;
; #pragma unroll
;             for (int c_ = 0; c_ < 2; ++c_)
; #pragma unroll
;                 for (int ks_ = 0; ks_ < 4; ++ks_) {
;                     const s16x4 lo_ = tr16(vb_ + (16 * ks_) * VP + 64 * c_), hi_ = tr16(vb_ + (16 * ks_ + 8) * VP + 64 * c_);
;                     const bf16x8 vf_ = {lo_[0], lo_[1], lo_[2], lo_[3], hi_[0], hi_[1], hi_[2], hi_[3]};
;                     o[c_] = mfma32(vf_, pf[ks_], o[c_]);
;                 }
.LBB0_323:
	v_sub_co_u32_e64 v10, vcc, s18, 32
	v_lshrrev_b32_e32 v0, s18, v160
	v_lshrrev_b32_e32 v10, v10, v161
	v_cndmask_b32_e32 v0, v10, v0, vcc
	v_and_b32_e32 v0, 1, v0
	v_cmp_eq_u32_e64 s[38:39], 1, v0
	v_cmp_ne_u32_e32 vcc, 0, v0
	s_cbranch_vccz .LBB0_331
	v_add_u32_e32 v14, v182, v183
	v_add_u32_e32 v0, v184, v183
	s_lshl_b32 s13, s18, 6
	v_cmp_ge_i32_e32 vcc, s13, v179
	v_add_u32_e32 v212, v186, v187
	ds_read_b128 v[64:67], v14 offset:9216
	ds_read_b128 v[68:71], v0 offset:9216
	ds_read_b128 v[72:75], v14 offset:9248
	ds_read_b128 v[76:79], v0 offset:9248
	ds_read_b128 v[80:83], v14 offset:9280
	ds_read_b128 v[84:87], v0 offset:9280
	ds_read_b128 v[88:91], v14 offset:9312
	ds_read_b128 v[92:95], v0 offset:9312
	s_waitcnt lgkmcnt(7)
	v_mfma_f32_32x32x16_bf16 v[112:127], v[64:67], v[128:131], v[48:63]
	ds_read_b64_tr_b16 v[196:197], v212 offset:30720
	ds_read_b64_tr_b16 v[198:199], v212 offset:32256
	s_waitcnt lgkmcnt(8)
	v_mfma_f32_32x32x16_bf16 v[96:111], v[68:71], v[128:131], v[48:63]
	ds_read_b64_tr_b16 v[200:201], v212 offset:33792
	ds_read_b64_tr_b16 v[202:203], v212 offset:35328
	s_waitcnt lgkmcnt(9)
	v_mfma_f32_32x32x16_bf16 v[112:127], v[72:75], v[132:135], v[112:127]
	ds_read_b64_tr_b16 v[204:205], v212 offset:36864
	ds_read_b64_tr_b16 v[206:207], v212 offset:38400
	s_waitcnt lgkmcnt(10)
	v_mfma_f32_32x32x16_bf16 v[96:111], v[76:79], v[132:135], v[96:111]
	ds_read_b64_tr_b16 v[208:209], v212 offset:39936
	ds_read_b64_tr_b16 v[210:211], v212 offset:41472
	s_waitcnt lgkmcnt(11)
	v_mfma_f32_32x32x16_bf16 v[112:127], v[80:83], v[136:139], v[112:127]
	ds_read_b64_tr_b16 v[238:239], v212 offset:30784
	ds_read_b64_tr_b16 v[240:241], v212 offset:32320
	s_waitcnt lgkmcnt(12)
	v_mfma_f32_32x32x16_bf16 v[96:111], v[84:87], v[136:139], v[96:111]
	ds_read_b64_tr_b16 v[242:243], v212 offset:33856
	ds_read_b64_tr_b16 v[244:245], v212 offset:35392
	s_waitcnt lgkmcnt(13)
	v_mfma_f32_32x32x16_bf16 v[112:127], v[88:91], v[140:143], v[112:127]
	ds_read_b64_tr_b16 v[246:247], v212 offset:36928
	ds_read_b64_tr_b16 v[248:249], v212 offset:38464
	s_waitcnt lgkmcnt(14)
	v_mfma_f32_32x32x16_bf16 v[96:111], v[92:95], v[140:143], v[96:111]
	ds_read_b64_tr_b16 v[234:235], v212 offset:40000
	ds_read_b64_tr_b16 v[236:237], v212 offset:41536
	s_and_saveexec_b64 s[0:1], vcc
	s_xor_b64 s[0:1], exec, s[0:1]
	s_cbranch_execz .LBB0_326
; template <int MODE> ...
;     ...
;         } else if (MODE == MODE_WIN || MODE == MODE_SEL) {
;             const int dbase = t - kbase;
;             const lptr tb = L + tabofs + (dbase + TAB0 - 63) * 4;
; #pragma unroll
;             for (int kb = 0; kb < 2; ++kb)
; #pragma unroll
;                 for (int a = 0; a < 4; ++a)
; #pragma unroll
;                     for (int e = 0; e < 4; ++e) {
;                         const int r = 4 * a + e, off = 32 * kb + 8 * a + e; const int d = dbase - off;
;                         const float bsv = far ? tab128 : lds_ld<float>(tb + 4 * (63 - off));
;                         const bool ok = (MODE == MODE_WIN) ? ((unsigned)d < (unsigned)W) : (selbit && d >= 0);
;                         const float sv = kb ? s1[r] : s0[r];
;                         const float x = ok ? sv * SC2 + bsv : -INFINITY;
;                         if (kb) s1[r] = x; else s0[r] = x;
;                     }
	v_or_b32_e32 v0, s13, v185
	v_sub_u32_e32 v0, v229, v0
	v_lshl_add_u32 v10, v0, 2, v230
	ds_read2_b32 v[12:13], v10 offset0:127 offset1:128
	v_cmp_lt_i32_e32 vcc, -1, v0
	s_and_b64 vcc, vcc, s[38:39]
	s_waitcnt lgkmcnt(0)
	s_nop 0
	v_fmamk_f32 v11, v112, 0x3e38aa3b, v13
	v_cndmask_b32_e32 v64, v220, v11, vcc
	v_cmp_lt_i32_e32 vcc, 0, v0
	s_and_b64 vcc, vcc, s[38:39]
	v_fmac_f32_e32 v12, 0x3e38aa3b, v113
	v_cndmask_b32_e32 v65, v220, v12, vcc
	ds_read2_b32 v[12:13], v10 offset0:125 offset1:126
	v_cmp_lt_i32_e32 vcc, 1, v0
	s_and_b64 vcc, vcc, s[38:39]
	s_waitcnt lgkmcnt(0)
	v_fmamk_f32 v11, v114, 0x3e38aa3b, v13
	v_cndmask_b32_e32 v66, v220, v11, vcc
	v_cmp_lt_i32_e32 vcc, 2, v0
	s_and_b64 vcc, vcc, s[38:39]
	v_fmac_f32_e32 v12, 0x3e38aa3b, v115
	v_cndmask_b32_e32 v67, v220, v12, vcc
	ds_read2_b32 v[12:13], v10 offset0:119 offset1:120
	v_cmp_lt_i32_e32 vcc, 7, v0
	s_and_b64 vcc, vcc, s[38:39]
	s_waitcnt lgkmcnt(0)
	v_fmamk_f32 v11, v116, 0x3e38aa3b, v13
	v_cndmask_b32_e32 v68, v220, v11, vcc
	v_cmp_lt_i32_e32 vcc, 8, v0
	s_and_b64 vcc, vcc, s[38:39]
	v_fmac_f32_e32 v12, 0x3e38aa3b, v117
	v_cndmask_b32_e32 v69, v220, v12, vcc
	ds_read2_b32 v[12:13], v10 offset0:117 offset1:118
	v_cmp_lt_i32_e32 vcc, 9, v0
	s_and_b64 vcc, vcc, s[38:39]
	s_waitcnt lgkmcnt(0)
	v_fmamk_f32 v11, v118, 0x3e38aa3b, v13
	v_cndmask_b32_e32 v70, v220, v11, vcc
	v_cmp_lt_i32_e32 vcc, 10, v0
	s_and_b64 vcc, vcc, s[38:39]
	v_fmac_f32_e32 v12, 0x3e38aa3b, v119
	v_cndmask_b32_e32 v71, v220, v12, vcc
	ds_read2_b32 v[12:13], v10 offset0:111 offset1:112
	v_cmp_lt_i32_e32 vcc, 15, v0
	s_and_b64 vcc, vcc, s[38:39]
	s_waitcnt lgkmcnt(0)
	v_fmamk_f32 v11, v120, 0x3e38aa3b, v13
	v_cndmask_b32_e32 v72, v220, v11, vcc
	v_cmp_lt_i32_e32 vcc, 16, v0
	s_and_b64 vcc, vcc, s[38:39]
	v_fmac_f32_e32 v12, 0x3e38aa3b, v121
	v_cndmask_b32_e32 v73, v220, v12, vcc
	ds_read2_b32 v[12:13], v10 offset0:109 offset1:110
	v_cmp_lt_i32_e32 vcc, 17, v0
	s_and_b64 vcc, vcc, s[38:39]
	s_waitcnt lgkmcnt(0)
	v_fmamk_f32 v11, v122, 0x3e38aa3b, v13
	v_cndmask_b32_e32 v74, v220, v11, vcc
	v_cmp_lt_i32_e32 vcc, 18, v0
	s_and_b64 vcc, vcc, s[38:39]
	v_fmac_f32_e32 v12, 0x3e38aa3b, v123
	v_cndmask_b32_e32 v75, v220, v12, vcc
	ds_read2_b32 v[12:13], v10 offset0:103 offset1:104
	v_cmp_lt_i32_e32 vcc, 23, v0
	s_and_b64 vcc, vcc, s[38:39]
	s_waitcnt lgkmcnt(0)
	v_fmamk_f32 v11, v124, 0x3e38aa3b, v13
	v_cndmask_b32_e32 v76, v220, v11, vcc
	v_cmp_lt_i32_e32 vcc, 24, v0
	s_and_b64 vcc, vcc, s[38:39]
	v_fmac_f32_e32 v12, 0x3e38aa3b, v125
	v_cndmask_b32_e32 v77, v220, v12, vcc
	ds_read2_b32 v[12:13], v10 offset0:101 offset1:102
	v_cmp_lt_i32_e32 vcc, 25, v0
	s_and_b64 vcc, vcc, s[38:39]
	s_waitcnt lgkmcnt(0)
	v_fmamk_f32 v11, v126, 0x3e38aa3b, v13
	v_cndmask_b32_e32 v78, v220, v11, vcc
	v_cmp_lt_i32_e32 vcc, 26, v0
	s_and_b64 vcc, vcc, s[38:39]
	v_fmac_f32_e32 v12, 0x3e38aa3b, v127
	v_cndmask_b32_e32 v79, v220, v12, vcc
	ds_read2_b32 v[12:13], v10 offset0:95 offset1:96
	v_cmp_lt_i32_e32 vcc, 31, v0
	s_and_b64 vcc, vcc, s[38:39]
	s_waitcnt lgkmcnt(0)
	v_fmamk_f32 v11, v96, 0x3e38aa3b, v13
	v_cndmask_b32_e32 v80, v220, v11, vcc
	v_cmp_lt_i32_e32 vcc, 32, v0
	s_and_b64 vcc, vcc, s[38:39]
	v_fmac_f32_e32 v12, 0x3e38aa3b, v97
	v_cndmask_b32_e32 v81, v220, v12, vcc
	ds_read2_b32 v[12:13], v10 offset0:93 offset1:94
	v_cmp_lt_i32_e32 vcc, 33, v0
	s_and_b64 vcc, vcc, s[38:39]
	s_waitcnt lgkmcnt(0)
	v_fmamk_f32 v11, v98, 0x3e38aa3b, v13
	v_cndmask_b32_e32 v82, v220, v11, vcc
	v_cmp_lt_i32_e32 vcc, 34, v0
	s_and_b64 vcc, vcc, s[38:39]
	v_fmac_f32_e32 v12, 0x3e38aa3b, v99
	v_cndmask_b32_e32 v83, v220, v12, vcc
	ds_read2_b32 v[12:13], v10 offset0:87 offset1:88
	v_cmp_lt_i32_e32 vcc, 39, v0
	s_and_b64 vcc, vcc, s[38:39]
	s_waitcnt lgkmcnt(0)
	v_fmamk_f32 v11, v100, 0x3e38aa3b, v13
	v_cndmask_b32_e32 v84, v220, v11, vcc
	v_cmp_lt_i32_e32 vcc, 40, v0
	s_and_b64 vcc, vcc, s[38:39]
	v_fmac_f32_e32 v12, 0x3e38aa3b, v101
	v_cndmask_b32_e32 v85, v220, v12, vcc
	ds_read2_b32 v[12:13], v10 offset0:85 offset1:86
	v_cmp_lt_i32_e32 vcc, 41, v0
	s_and_b64 vcc, vcc, s[38:39]
	s_waitcnt lgkmcnt(0)
	v_fmamk_f32 v11, v102, 0x3e38aa3b, v13
	v_cndmask_b32_e32 v86, v220, v11, vcc
	v_cmp_lt_i32_e32 vcc, 42, v0
	s_and_b64 vcc, vcc, s[38:39]
	v_fmac_f32_e32 v12, 0x3e38aa3b, v103
	v_cndmask_b32_e32 v87, v220, v12, vcc
	ds_read2_b32 v[12:13], v10 offset0:79 offset1:80
	v_cmp_lt_i32_e32 vcc, 47, v0
	s_and_b64 vcc, vcc, s[38:39]
	s_waitcnt lgkmcnt(0)
	v_fmamk_f32 v11, v104, 0x3e38aa3b, v13
	v_cndmask_b32_e32 v88, v220, v11, vcc
	v_cmp_lt_i32_e32 vcc, 48, v0
	s_and_b64 vcc, vcc, s[38:39]
	v_fmac_f32_e32 v12, 0x3e38aa3b, v105
	v_cndmask_b32_e32 v89, v220, v12, vcc
	ds_read2_b32 v[12:13], v10 offset0:77 offset1:78
	v_cmp_lt_i32_e32 vcc, 49, v0
	s_and_b64 vcc, vcc, s[38:39]
	s_waitcnt lgkmcnt(0)
	v_fmamk_f32 v11, v106, 0x3e38aa3b, v13
	v_cndmask_b32_e32 v90, v220, v11, vcc
	v_cmp_lt_i32_e32 vcc, 50, v0
	s_and_b64 vcc, vcc, s[38:39]
	v_fmac_f32_e32 v12, 0x3e38aa3b, v107
	v_cndmask_b32_e32 v91, v220, v12, vcc
	ds_read2_b32 v[12:13], v10 offset0:71 offset1:72
	v_cmp_lt_i32_e32 vcc, 55, v0
	s_and_b64 vcc, vcc, s[38:39]
	s_waitcnt lgkmcnt(0)
	v_fmamk_f32 v11, v108, 0x3e38aa3b, v13
	v_cndmask_b32_e32 v92, v220, v11, vcc
	ds_read2_b32 v[10:11], v10 offset0:69 offset1:70
	v_cmp_lt_i32_e32 vcc, 56, v0
	s_and_b64 vcc, vcc, s[38:39]
	v_fmac_f32_e32 v12, 0x3e38aa3b, v109
	v_cndmask_b32_e32 v93, v220, v12, vcc
	v_cmp_lt_i32_e32 vcc, 57, v0
	s_and_b64 vcc, vcc, s[38:39]
	s_waitcnt lgkmcnt(0)
	v_fmamk_f32 v11, v110, 0x3e38aa3b, v11
	v_cndmask_b32_e32 v94, v220, v11, vcc
	v_cmp_lt_i32_e32 vcc, 58, v0
	s_and_b64 vcc, vcc, s[38:39]
	v_fmac_f32_e32 v10, 0x3e38aa3b, v111
	v_cndmask_b32_e32 v95, v220, v10, vcc

; __device__ __forceinline__ f32x16 mfma32(bf16x8 a, bf16x8 b, f32x16 c) { return __builtin_amdgcn_mfma_f32_32x32x16_bf16(a, b, c, 0, 0, 0); }
; __device__ __forceinline__ s16x4 tr16(lptr p) { return __builtin_bit_cast(s16x4, __builtin_amdgcn_ds_read_tr16_b64_v4i16((LAS v4i16_t*)p)); }
; template <int MODE> ...
;     ...
;         const lptr Kt = L + A_KT + buf * 9216, Vt = L + A_VT + vcur * 12288;
;         f32x16 s0, s1;
; #pragma unroll
;         for (int s4 = 0; s4 < 4; ++s4) {
;             const bf16x8 a0 = lds_ld<bf16x8>(Kt + n * KP + s4 * 32 + hl * 16);
;             const bf16x8 a1 = lds_ld<bf16x8>(Kt + (32 + n) * KP + s4 * 32 + hl * 16);
;             if (s4 == 0) { s0 = mfma32(a0, qf[0], negm); s1 = mfma32(a1, qf[0], negm); }
;             else { s0 = mfma32(a0, qf[s4], s0); s1 = mfma32(a1, qf[s4], s1); }
;         }
;         const int kbase = 64 * kt + 4 * hl;
;         const bool far = (MODE == MODE_WIN || MODE == MODE_SEL) ? (wtmin - (64 * kt + 63) >= 128) : false;
;         const bool fmask = (MODE == MODE_FOX) ? (64 * kt + 63 > wtmin) : false;
;         const bool clean = (MODE == MODE_WIN) ? (far && (wtmax - 64 * kt < W)) : false;
;     ...
;             const lptr vb_ = Vt + (4 * hl + q4) * VP + 32 * blk + 8 * p4;
; #pragma unroll
;             for (int c_ = 0; c_ < 2; ++c_)
; #pragma unroll
;                 for (int ks_ = 0; ks_ < 4; ++ks_) {
;                     const s16x4 lo_ = tr16(vb_ + (16 * ks_) * VP + 64 * c_), hi_ = tr16(vb_ + (16 * ks_ + 8) * VP + 64 * c_);
;                     const bf16x8 vf_ = {lo_[0], lo_[1], lo_[2], lo_[3], hi_[0], hi_[1], hi_[2], hi_[3]};
;                     o[c_] = mfma32(vf_, pf[ks_], o[c_]);
;                 }
.LBB0_344:
	s_lshl_b32 s6, s0, 6
	v_cmp_ge_i32_e32 vcc, s6, v186
	v_cmp_le_i32_e64 s[0:1], s6, v187
	s_or_b64 s[0:1], vcc, s[0:1]
	ds_read_b128 v[80:83], v191 offset:0
	ds_read_b128 v[84:87], v190 offset:0
	ds_read_b128 v[88:91], v191 offset:32
	ds_read_b128 v[92:95], v190 offset:32
	ds_read_b128 v[96:99], v191 offset:64
	ds_read_b128 v[100:103], v190 offset:64
	ds_read_b128 v[104:107], v191 offset:96
	ds_read_b128 v[108:111], v190 offset:96
	s_waitcnt lgkmcnt(7)
	v_mfma_f32_32x32x16_bf16 v[112:127], v[80:83], v[128:131], v[48:63]
	ds_read_b64_tr_b16 v[196:197], v192 offset:18432
	ds_read_b64_tr_b16 v[198:199], v192 offset:19968
	s_waitcnt lgkmcnt(8)
	v_mfma_f32_32x32x16_bf16 v[64:79], v[84:87], v[128:131], v[48:63]
	ds_read_b64_tr_b16 v[200:201], v192 offset:21504
	ds_read_b64_tr_b16 v[202:203], v192 offset:23040
	s_waitcnt lgkmcnt(9)
	v_mfma_f32_32x32x16_bf16 v[112:127], v[88:91], v[132:135], v[112:127]
	ds_read_b64_tr_b16 v[204:205], v192 offset:24576
	ds_read_b64_tr_b16 v[206:207], v192 offset:26112
	s_waitcnt lgkmcnt(10)
	v_mfma_f32_32x32x16_bf16 v[64:79], v[92:95], v[132:135], v[64:79]
	ds_read_b64_tr_b16 v[208:209], v192 offset:27648
	ds_read_b64_tr_b16 v[210:211], v192 offset:29184
	s_waitcnt lgkmcnt(11)
	v_mfma_f32_32x32x16_bf16 v[112:127], v[96:99], v[136:139], v[112:127]
	ds_read_b64_tr_b16 v[238:239], v192 offset:18496
	ds_read_b64_tr_b16 v[240:241], v192 offset:20032
	s_waitcnt lgkmcnt(12)
	v_mfma_f32_32x32x16_bf16 v[64:79], v[100:103], v[136:139], v[64:79]
	ds_read_b64_tr_b16 v[242:243], v192 offset:21568
	ds_read_b64_tr_b16 v[244:245], v192 offset:23104
	s_waitcnt lgkmcnt(13)
	v_mfma_f32_32x32x16_bf16 v[112:127], v[104:107], v[140:143], v[112:127]
	ds_read_b64_tr_b16 v[246:247], v192 offset:24640
	ds_read_b64_tr_b16 v[248:249], v192 offset:26176
	s_waitcnt lgkmcnt(14)
	v_mfma_f32_32x32x16_bf16 v[64:79], v[108:111], v[140:143], v[64:79]
	ds_read_b64_tr_b16 v[234:235], v192 offset:27712
	ds_read_b64_tr_b16 v[236:237], v192 offset:29248
	s_and_saveexec_b64 s[38:39], s[0:1]
	s_xor_b64 s[0:1], exec, s[38:39]
	s_cbranch_execz .LBB0_379
	v_or_b32_e32 v0, s6, v145
	v_sub_u32_e32 v0, v229, v0
	v_lshlrev_b32_e32 v10, 2, v0
	v_add_u32_e32 v80, v230, v10
	v_mov_b32_e32 v10, v146
	s_and_saveexec_b64 s[6:7], vcc
	s_cbranch_execnz .LBB0_431
	s_or_b64 exec, exec, s[6:7]
	v_mov_b32_e32 v11, v146
	s_and_saveexec_b64 s[6:7], vcc
	s_cbranch_execnz .LBB0_432

; __device__ __forceinline__ f32x16 mfma32(bf16x8 a, bf16x8 b, f32x16 c) { return __builtin_amdgcn_mfma_f32_32x32x16_bf16(a, b, c, 0, 0, 0); }
; __device__ __forceinline__ s16x4 tr16(lptr p) { return __builtin_bit_cast(s16x4, __builtin_amdgcn_ds_read_tr16_b64_v4i16((LAS v4i16_t*)p)); }
; template <int MODE> ...
;     ...
;         const lptr Kt = L + A_KT + buf * 9216, Vt = L + A_VT + vcur * 12288;
;         f32x16 s0, s1;
; #pragma unroll
;         for (int s4 = 0; s4 < 4; ++s4) {
;             const bf16x8 a0 = lds_ld<bf16x8>(Kt + n * KP + s4 * 32 + hl * 16);
;             const bf16x8 a1 = lds_ld<bf16x8>(Kt + (32 + n) * KP + s4 * 32 + hl * 16);
;             if (s4 == 0) { s0 = mfma32(a0, qf[0], negm); s1 = mfma32(a1, qf[0], negm); }
;             else { s0 = mfma32(a0, qf[s4], s0); s1 = mfma32(a1, qf[s4], s1); }
;         }
;         const int kbase = 64 * kt + 4 * hl;
;         const bool far = (MODE == MODE_WIN || MODE == MODE_SEL) ? (wtmin - (64 * kt + 63) >= 128) : false;
;         const bool fmask = (MODE == MODE_FOX) ? (64 * kt + 63 > wtmin) : false;
;         const bool clean = (MODE == MODE_WIN) ? (far && (wtmax - 64 * kt < W)) : false;
;     ...
;             const lptr vb_ = Vt + (4 * hl + q4) * VP + 32 * blk + 8 * p4;
; #pragma unroll
;             for (int c_ = 0; c_ < 2; ++c_)
; #pragma unroll
;                 for (int ks_ = 0; ks_ < 4; ++ks_) {
;                     const s16x4 lo_ = tr16(vb_ + (16 * ks_) * VP + 64 * c_), hi_ = tr16(vb_ + (16 * ks_ + 8) * VP + 64 * c_);
;                     const bf16x8 vf_ = {lo_[0], lo_[1], lo_[2], lo_[3], hi_[0], hi_[1], hi_[2], hi_[3]};
;                     o[c_] = mfma32(vf_, pf[ks_], o[c_]);
;                 }
.LBB0_389:
	s_lshl_b32 s6, s18, 6
	v_cmp_ge_i32_e32 vcc, s6, v186
	v_cmp_le_i32_e64 s[0:1], s6, v187
	s_or_b64 s[0:1], vcc, s[0:1]
	ds_read_b128 v[80:83], v191 offset:9216
	ds_read_b128 v[84:87], v190 offset:9216
	ds_read_b128 v[88:91], v191 offset:9248
	ds_read_b128 v[92:95], v190 offset:9248
	ds_read_b128 v[96:99], v191 offset:9280
	ds_read_b128 v[100:103], v190 offset:9280
	ds_read_b128 v[104:107], v191 offset:9312
	ds_read_b128 v[108:111], v190 offset:9312
	s_waitcnt lgkmcnt(7)
	v_mfma_f32_32x32x16_bf16 v[112:127], v[80:83], v[128:131], v[64:79]
	ds_read_b64_tr_b16 v[196:197], v192 offset:30720
	ds_read_b64_tr_b16 v[198:199], v192 offset:32256
	s_waitcnt lgkmcnt(8)
	v_mfma_f32_32x32x16_bf16 v[64:79], v[84:87], v[128:131], v[64:79]
	ds_read_b64_tr_b16 v[200:201], v192 offset:33792
	ds_read_b64_tr_b16 v[202:203], v192 offset:35328
	s_waitcnt lgkmcnt(9)
	v_mfma_f32_32x32x16_bf16 v[112:127], v[88:91], v[132:135], v[112:127]
	ds_read_b64_tr_b16 v[204:205], v192 offset:36864
	ds_read_b64_tr_b16 v[206:207], v192 offset:38400
	s_waitcnt lgkmcnt(10)
	v_mfma_f32_32x32x16_bf16 v[64:79], v[92:95], v[132:135], v[64:79]
	ds_read_b64_tr_b16 v[208:209], v192 offset:39936
	ds_read_b64_tr_b16 v[210:211], v192 offset:41472
	s_waitcnt lgkmcnt(11)
	v_mfma_f32_32x32x16_bf16 v[112:127], v[96:99], v[136:139], v[112:127]
	ds_read_b64_tr_b16 v[238:239], v192 offset:30784
	ds_read_b64_tr_b16 v[240:241], v192 offset:32320
	s_waitcnt lgkmcnt(12)
	v_mfma_f32_32x32x16_bf16 v[64:79], v[100:103], v[136:139], v[64:79]
	ds_read_b64_tr_b16 v[242:243], v192 offset:33856
	ds_read_b64_tr_b16 v[244:245], v192 offset:35392
	s_waitcnt lgkmcnt(13)
	v_mfma_f32_32x32x16_bf16 v[112:127], v[104:107], v[140:143], v[112:127]
	ds_read_b64_tr_b16 v[246:247], v192 offset:36928
	ds_read_b64_tr_b16 v[248:249], v192 offset:38464
	s_waitcnt lgkmcnt(14)
	v_mfma_f32_32x32x16_bf16 v[64:79], v[108:111], v[140:143], v[64:79]
	ds_read_b64_tr_b16 v[234:235], v192 offset:40000
	ds_read_b64_tr_b16 v[236:237], v192 offset:41536
	s_and_saveexec_b64 s[38:39], s[0:1]
	s_xor_b64 s[0:1], exec, s[38:39]
	s_cbranch_execz .LBB0_424
	v_or_b32_e32 v0, s6, v145
	v_sub_u32_e32 v0, v229, v0
	v_lshlrev_b32_e32 v10, 2, v0
	v_add_u32_e32 v80, v230, v10
	v_mov_b32_e32 v10, v146
	s_and_saveexec_b64 s[6:7], vcc
	s_cbranch_execnz .LBB0_462
	s_or_b64 exec, exec, s[6:7]
	v_mov_b32_e32 v11, v146
	s_and_saveexec_b64 s[6:7], vcc
	s_cbranch_execnz .LBB0_463
